# p3headstart: LoRA blocks (which have slack) sleep ~3.4us at P3 start so the long-pole K/V GEMM blocks get the memory system first; on p3scanbal2
# speedup vs baseline: 1.0073x; 1.0016x over previous
.LBB0_530:
	s_and_b64 vcc, exec, s[0:1]
	s_cbranch_vccz .LBB0_583
	s_cmp_lt_u32 s69, 64
	s_cbranch_scc1 .Lp3d_skip
	s_mov_b32 s101, 1
.Lp3d_loop:
	s_sleep 127
	s_sub_u32 s101, s101, 1
	s_cmp_lg_u32 s101, 0
	s_cbranch_scc1 .Lp3d_loop
.Lp3d_skip:
	s_cmp_gt_i32 s69, 31
	s_mov_b64 s[0:1], -1
	s_cbranch_scc0 .LBB0_562
	s_cmp_gt_u32 s69, 63
	s_cbranch_scc0 .LBB0_554
	s_sub_i32 s36, s69, 64
	s_cmpk_gt_u32 s36, 0x2ff
	v_readfirstlane_b32 s37, v170
	s_cbranch_scc1 .LBB0_553
	v_lshrrev_b32_e32 v0, 5, v170
	v_lshrrev_b32_e32 v2, 1, v170
	v_and_b32_e32 v0, 4, v0
	v_bfe_u32 v1, v170, 2, 2
	v_and_b32_e32 v11, 24, v2
	v_or3_b32 v0, v0, v1, v11
	v_lshlrev_b32_e32 v1, 4, v170
	v_add_u32_e32 v8, 0x2000, v1
	v_lshrrev_b32_e32 v2, 7, v8
	s_movk_i32 s0, 0xe0
	v_and_b32_e32 v4, 32, v170
	v_and_or_b32 v3, v2, s0, v0
	v_bitop3_b32 v9, v1, v4, 48 bitop3:0x6c
	v_and_b32_e32 v10, 64, v170
	v_bfe_u32 v12, v170, 2, 4
	s_movk_i32 s0, 0xf0
	v_or_b32_e32 v1, v9, v10
	v_and_or_b32 v2, v2, s0, v12
	v_lshl_or_b32 v146, v2, 10, v1
	v_lshrrev_b32_e32 v2, 3, v170
	s_movk_i32 s0, 0x60
	s_add_u32 s40, s66, 0x8000000
	v_and_or_b32 v0, v2, s0, v0
	s_movk_i32 s0, 0x70
	s_addc_u32 s41, s67, 0
	v_lshl_or_b32 v148, v0, 10, v1
	v_and_or_b32 v0, v2, s0, v12
	s_and_b32 s0, s69, 7
	s_lshr_b32 s1, s36, 3
	s_mulk_i32 s0, 0x60
	s_add_i32 s0, s0, s1
	s_mul_i32 s1, s0, 0xaaab
	s_lshr_b32 s1, s1, 21
	s_lshl_b32 s12, s1, 2
	s_mul_i32 s1, s1, 48
	s_sub_i32 s0, s0, s1
	s_and_b32 s1, s0, 3
	s_lshr_b32 s2, s37, 6
	s_or_b32 s12, s12, s1
	s_bfe_u32 s13, s0, 0x60002
	s_lshr_b32 s3, s37, 8
	s_lshl_b32 s42, s2, 10
	s_lshl_b32 s0, s12, 18
	s_lshl_b32 s1, s13, 18
	s_lshr_b32 s98, s13, 2
	s_add_i32 s99, s98, 1
	s_mul_i32 s98, s98, s99
	s_lshl_b32 s98, s98, 6
	s_add_i32 s0, s0, s98
	s_add_i32 s1, s1, s98
	s_add_u32 s30, s40, s1
	s_addc_u32 s31, s41, 0
	s_add_i32 s43, s42, 0
	s_add_i32 m0, s43, 0x10000
	v_lshl_or_b32 v144, v3, 10, v1
	global_load_lds_dwordx4 v148, s[30:31]
	s_add_i32 m0, s43, 0x12000
	s_add_u32 s0, s38, s0
	v_lshl_or_b32 v150, v0, 10, v1
	global_load_lds_dwordx4 v144, s[30:31]
	s_addc_u32 s1, s39, 0
	s_mov_b32 m0, s43
	s_add_i32 s44, s43, 0x2000
	global_load_lds_dwordx4 v150, s[0:1]
	s_mov_b32 m0, s44
	s_add_u32 s14, s30, 0x20000
	global_load_lds_dwordx4 v146, s[0:1]
	s_addc_u32 s15, s31, 0
	s_add_i32 m0, s43, 0x14000
	v_mov_b32_e32 v153, 0
	global_load_lds_dwordx4 v148, s[14:15]
	s_add_i32 m0, s43, 0x16000
	v_mov_b32_e32 v149, v153
	global_load_lds_dwordx4 v144, s[14:15]
	s_add_u32 s14, s0, 0x20000
	s_addc_u32 s15, s1, 0
	s_add_i32 s45, s43, 0x4000
	s_mov_b32 m0, s45
	s_add_i32 s46, s43, 0x6000
	global_load_lds_dwordx4 v150, s[14:15]
	s_mov_b32 m0, s46
	v_mov_b32_e32 v145, v153
	global_load_lds_dwordx4 v146, s[14:15]
	v_mov_b32_e32 v151, v153
	v_mov_b32_e32 v147, v153
	s_mov_b32 s47, 0
	v_lshl_add_u64 v[6:7], s[30:31], 0, v[148:149]
	v_lshl_add_u64 v[4:5], s[30:31], 0, v[144:145]
	v_lshl_add_u64 v[2:3], s[0:1], 0, v[150:151]
	s_cmp_lg_u32 s3, 1
	v_lshl_add_u64 v[0:1], s[0:1], 0, v[146:147]
	s_cbranch_scc1 .LBB0_536
	s_barrier
